# k2 work queue: next unit index fetched one unit ahead (atomic round trip overlapped with the current unit)
# baseline (speedup 1.0000x reference)
_Z10fwd_kernelILi2ELi3EEv4Args:
	s_mov_b64 s[40:41], s[0:1]
	s_load_dword s0, s[0:1], 0xe8
	v_cmp_eq_u32_e64 s[4:5], 0, v0
	s_waitcnt lgkmcnt(0)
	s_and_b32 s1, s2, 15
	s_and_b32 s0, s0, 15
	v_writelane_b32 v251, s4, 0
	s_lshl_b32 s2, s1, 8
	s_cmp_eq_u32 s0, 0
	v_writelane_b32 v251, s5, 1
	v_writelane_b32 v251, s1, 2
	s_mov_b64 s[0:1], s[40:41]
	s_load_dwordx2 s[0:1], s[0:1], 0xd8
	s_cselect_b64 s[4:5], -1, 0
	v_writelane_b32 v251, s4, 3
	s_movk_i32 s6, 0x44
	s_mov_b32 s80, 0x41000000
	v_writelane_b32 v251, s5, 4
	s_and_b64 s[4:5], s[4:5], exec
	s_cselect_b32 s2, s2, 0
	s_cselect_b32 s95, s6, 0x440
	s_waitcnt lgkmcnt(0)
	s_add_u32 s0, s0, s2
	s_addc_u32 s1, s1, 0
	s_add_u32 s0, s0, 0x4000
	s_addc_u32 s1, s1, 0
	v_writelane_b32 v251, s0, 5
	v_mbcnt_lo_u32_b32 v2, -1, 0
	s_mov_b32 s3, 0
	v_writelane_b32 v251, s1, 6
	s_add_i32 s0, 0, 0x20080
	v_writelane_b32 v251, s0, 7
	v_mov_b32_e32 v1, s0
	s_add_i32 s0, 0, 0x12a00
	v_writelane_b32 v251, s0, 8
	v_mov_b32_e32 v99, 0
	s_movk_i32 s91, 0x1800
	s_movk_i32 s42, 0x110
	s_mov_b32 s81, 0x41100000
	v_mov_b32_e32 v237, 0x358637bd
	v_mov_b32_e32 v238, 0xff800000
	v_mbcnt_hi_u32_b32 v239, -1, v2
	v_mov_b32_e32 v240, 0x7f800000
	s_mov_b64 s[98:99], 0xc0000
	s_mov_b64 s[76:77], 0x40000
	v_writelane_b32 v251, s40, 9
	s_nop 1
	v_writelane_b32 v251, s41, 10
	s_mov_b64 s[0:1], exec
	v_readlane_b32 s4, v251, 0
	v_readlane_b32 s5, v251, 1
	s_and_b64 s[4:5], s[0:1], s[4:5]
	s_mov_b64 exec, s[4:5]
	s_cbranch_execz .Lq2_nofetch
	v_readlane_b32 s6, v251, 5
	v_mov_b32_e32 v253, 1
	v_readlane_b32 s7, v251, 6
	s_nop 4
	global_atomic_add v252, v99, v253, s[6:7] sc0
.Lq2_nofetch:
	s_mov_b64 exec, s[0:1]
	s_branch .LBB2_4

.LBB2_4:
	s_barrier
	s_mov_b64 s[0:1], exec
	v_readlane_b32 s4, v251, 0
	v_readlane_b32 s5, v251, 1
	s_and_b64 s[4:5], s[0:1], s[4:5]
	s_mov_b64 exec, s[4:5]
	s_cbranch_execz .LBB2_8
	s_mov_b64 s[6:7], exec
	v_mbcnt_lo_u32_b32 v2, s6, 0
	v_mbcnt_hi_u32_b32 v2, s7, v2
	v_cmp_eq_u32_e32 vcc, 0, v2
	s_and_saveexec_b64 s[4:5], vcc
	s_cbranch_execz .LBB2_7
	s_bcnt1_i32_b64 s2, s[6:7]
	v_readlane_b32 s6, v251, 5
	v_mov_b32_e32 v253, s2
	v_readlane_b32 s7, v251, 6
	s_waitcnt vmcnt(0)
	v_mov_b32_e32 v3, v252
	s_nop 4
	global_atomic_add v252, v99, v253, s[6:7] sc0
.LBB2_7:
	s_or_b64 exec, exec, s[4:5]
	v_readfirstlane_b32 s2, v3
	s_nop 1
	v_add_u32_e32 v2, s2, v2
	v_readlane_b32 s2, v251, 7
	s_nop 1
	v_mov_b32_e32 v3, s2
	ds_write_b32 v3, v2

	.amdhsa_kernel _Z10fwd_kernelILi2ELi3EEv4Args
		.amdhsa_group_segment_fixed_size 0
		.amdhsa_private_segment_fixed_size 0
		.amdhsa_kernarg_size 488
		.amdhsa_user_sgpr_count 2
		.amdhsa_user_sgpr_dispatch_ptr 0
		.amdhsa_user_sgpr_queue_ptr 0
		.amdhsa_user_sgpr_kernarg_segment_ptr 1
		.amdhsa_user_sgpr_dispatch_id 0
		.amdhsa_user_sgpr_kernarg_preload_length 0
		.amdhsa_user_sgpr_kernarg_preload_offset 0
		.amdhsa_user_sgpr_private_segment_size 0
		.amdhsa_uses_dynamic_stack 0
		.amdhsa_enable_private_segment 0
		.amdhsa_system_sgpr_workgroup_id_x 1
		.amdhsa_system_sgpr_workgroup_id_y 0
		.amdhsa_system_sgpr_workgroup_id_z 0
		.amdhsa_system_sgpr_workgroup_info 0
		.amdhsa_system_vgpr_workitem_id 0
		.amdhsa_next_free_vgpr 256
		.amdhsa_next_free_sgpr 100
		.amdhsa_accum_offset 256
		.amdhsa_reserve_vcc 1
		.amdhsa_float_round_mode_32 0
		.amdhsa_float_round_mode_16_64 0
		.amdhsa_float_denorm_mode_32 3
		.amdhsa_float_denorm_mode_16_64 3
		.amdhsa_dx10_clamp 1
		.amdhsa_ieee_mode 1
		.amdhsa_fp16_overflow 0
		.amdhsa_tg_split 0
		.amdhsa_exception_fp_ieee_invalid_op 0
		.amdhsa_exception_fp_denorm_src 0
		.amdhsa_exception_fp_ieee_div_zero 0
		.amdhsa_exception_fp_ieee_overflow 0
		.amdhsa_exception_fp_ieee_underflow 0
		.amdhsa_exception_fp_ieee_inexact 0
		.amdhsa_exception_int_div_zero 0
	.end_amdhsa_kernel

amdhsa.kernels:
  - .agpr_count:     0
    .args:
      - .offset:         0
        .size:           232
        .value_kind:     by_value
      - .offset:         232
        .size:           4
        .value_kind:     hidden_block_count_x
      - .offset:         236
        .size:           4
        .value_kind:     hidden_block_count_y
      - .offset:         240
        .size:           4
        .value_kind:     hidden_block_count_z
      - .offset:         244
        .size:           2
        .value_kind:     hidden_group_size_x
      - .offset:         246
        .size:           2
        .value_kind:     hidden_group_size_y
      - .offset:         248
        .size:           2
        .value_kind:     hidden_group_size_z
      - .offset:         250
        .size:           2
        .value_kind:     hidden_remainder_x
      - .offset:         252
        .size:           2
        .value_kind:     hidden_remainder_y
      - .offset:         254
        .size:           2
        .value_kind:     hidden_remainder_z
      - .offset:         272
        .size:           8
        .value_kind:     hidden_global_offset_x
      - .offset:         280
        .size:           8
        .value_kind:     hidden_global_offset_y
      - .offset:         288
        .size:           8
        .value_kind:     hidden_global_offset_z
      - .offset:         296
        .size:           2
        .value_kind:     hidden_grid_dims
      - .offset:         352
        .size:           4
        .value_kind:     hidden_dynamic_lds_size
    .group_segment_fixed_size: 0
    .kernarg_segment_align: 8
    .kernarg_segment_size: 488
    .language:       OpenCL C
    .language_version:
      - 2
      - 0
    .max_flat_workgroup_size: 512
    .name:           _Z10fwd_kernelILi0ELi1EEv4Args
    .private_segment_fixed_size: 0
    .sgpr_count:     106
    .sgpr_spill_count: 0
    .symbol:         _Z10fwd_kernelILi0ELi1EEv4Args.kd
    .uniform_work_group_size: 1
    .uses_dynamic_stack: false
    .vgpr_count:     224
    .vgpr_spill_count: 0
    .wavefront_size: 64
  - .agpr_count:     0
    .args:
      - .offset:         0
        .size:           232
        .value_kind:     by_value
      - .offset:         232
        .size:           4
        .value_kind:     hidden_block_count_x
      - .offset:         236
        .size:           4
        .value_kind:     hidden_block_count_y
      - .offset:         240
        .size:           4
        .value_kind:     hidden_block_count_z
      - .offset:         244
        .size:           2
        .value_kind:     hidden_group_size_x
      - .offset:         246
        .size:           2
        .value_kind:     hidden_group_size_y
      - .offset:         248
        .size:           2
        .value_kind:     hidden_group_size_z
      - .offset:         250
        .size:           2
        .value_kind:     hidden_remainder_x
      - .offset:         252
        .size:           2
        .value_kind:     hidden_remainder_y
      - .offset:         254
        .size:           2
        .value_kind:     hidden_remainder_z
      - .offset:         272
        .size:           8
        .value_kind:     hidden_global_offset_x
      - .offset:         280
        .size:           8
        .value_kind:     hidden_global_offset_y
      - .offset:         288
        .size:           8
        .value_kind:     hidden_global_offset_z
      - .offset:         296
        .size:           2
        .value_kind:     hidden_grid_dims
      - .offset:         352
        .size:           4
        .value_kind:     hidden_dynamic_lds_size
    .group_segment_fixed_size: 0
    .kernarg_segment_align: 8
    .kernarg_segment_size: 488
    .language:       OpenCL C
    .language_version:
      - 2
      - 0
    .max_flat_workgroup_size: 512
    .name:           _Z10fwd_kernelILi1ELi2EEv4Args
    .private_segment_fixed_size: 0
    .sgpr_count:     64
    .sgpr_spill_count: 0
    .symbol:         _Z10fwd_kernelILi1ELi2EEv4Args.kd
    .uniform_work_group_size: 1
    .uses_dynamic_stack: false
    .vgpr_count:     256
    .vgpr_spill_count: 0
    .wavefront_size: 64
  - .agpr_count:     0
    .args:
      - .offset:         0
        .size:           232
        .value_kind:     by_value
      - .offset:         232
        .size:           4
        .value_kind:     hidden_block_count_x
      - .offset:         236
        .size:           4
        .value_kind:     hidden_block_count_y
      - .offset:         240
        .size:           4
        .value_kind:     hidden_block_count_z
      - .offset:         244
        .size:           2
        .value_kind:     hidden_group_size_x
      - .offset:         246
        .size:           2
        .value_kind:     hidden_group_size_y
      - .offset:         248
        .size:           2
        .value_kind:     hidden_group_size_z
      - .offset:         250
        .size:           2
        .value_kind:     hidden_remainder_x
      - .offset:         252
        .size:           2
        .value_kind:     hidden_remainder_y
      - .offset:         254
        .size:           2
        .value_kind:     hidden_remainder_z
      - .offset:         272
        .size:           8
        .value_kind:     hidden_global_offset_x
      - .offset:         280
        .size:           8
        .value_kind:     hidden_global_offset_y
      - .offset:         288
        .size:           8
        .value_kind:     hidden_global_offset_z
      - .offset:         296
        .size:           2
        .value_kind:     hidden_grid_dims
      - .offset:         352
        .size:           4
        .value_kind:     hidden_dynamic_lds_size
    .group_segment_fixed_size: 0
    .kernarg_segment_align: 8
    .kernarg_segment_size: 488
    .language:       OpenCL C
    .language_version:
      - 2
      - 0
    .max_flat_workgroup_size: 512
    .name:           _Z10fwd_kernelILi2ELi3EEv4Args
    .private_segment_fixed_size: 0
    .sgpr_count:     106
    .sgpr_spill_count: 11
    .symbol:         _Z10fwd_kernelILi2ELi3EEv4Args.kd
    .uniform_work_group_size: 1
    .uses_dynamic_stack: false
    .vgpr_count:     256
    .vgpr_spill_count: 0
    .wavefront_size: 64
  - .agpr_count:     0
    .args:
      - .offset:         0
        .size:           232
        .value_kind:     by_value
      - .offset:         232
        .size:           4
        .value_kind:     hidden_block_count_x
      - .offset:         236
        .size:           4
        .value_kind:     hidden_block_count_y
      - .offset:         240
        .size:           4
        .value_kind:     hidden_block_count_z
      - .offset:         244
        .size:           2
        .value_kind:     hidden_group_size_x
      - .offset:         246
        .size:           2
        .value_kind:     hidden_group_size_y
      - .offset:         248
        .size:           2
        .value_kind:     hidden_group_size_z
      - .offset:         250
        .size:           2
        .value_kind:     hidden_remainder_x
      - .offset:         252
        .size:           2
        .value_kind:     hidden_remainder_y
      - .offset:         254
        .size:           2
        .value_kind:     hidden_remainder_z
      - .offset:         272
        .size:           8
        .value_kind:     hidden_global_offset_x
      - .offset:         280
        .size:           8
        .value_kind:     hidden_global_offset_y
      - .offset:         288
        .size:           8
        .value_kind:     hidden_global_offset_z
      - .offset:         296
        .size:           2
        .value_kind:     hidden_grid_dims
      - .offset:         352
        .size:           4
        .value_kind:     hidden_dynamic_lds_size
    .group_segment_fixed_size: 0
    .kernarg_segment_align: 8
    .kernarg_segment_size: 488
    .language:       OpenCL C
    .language_version:
      - 2
      - 0
    .max_flat_workgroup_size: 512
    .name:           _Z10fwd_kernelILi3ELi4EEv4Args
    .private_segment_fixed_size: 0
    .sgpr_count:     67
    .sgpr_spill_count: 0
    .symbol:         _Z10fwd_kernelILi3ELi4EEv4Args.kd
    .uniform_work_group_size: 1
    .uses_dynamic_stack: false
    .vgpr_count:     240
    .vgpr_spill_count: 0
    .wavefront_size: 64
  - .agpr_count:     0
    .args:
      - .offset:         0
        .size:           232
        .value_kind:     by_value
      - .offset:         232
        .size:           4
        .value_kind:     hidden_block_count_x
      - .offset:         236
        .size:           4
        .value_kind:     hidden_block_count_y
      - .offset:         240
        .size:           4
        .value_kind:     hidden_block_count_z
      - .offset:         244
        .size:           2
        .value_kind:     hidden_group_size_x
      - .offset:         246
        .size:           2
        .value_kind:     hidden_group_size_y
      - .offset:         248
        .size:           2
        .value_kind:     hidden_group_size_z
      - .offset:         250
        .size:           2
        .value_kind:     hidden_remainder_x
      - .offset:         252
        .size:           2
        .value_kind:     hidden_remainder_y
      - .offset:         254
        .size:           2
        .value_kind:     hidden_remainder_z
      - .offset:         272
        .size:           8
        .value_kind:     hidden_global_offset_x
      - .offset:         280
        .size:           8
        .value_kind:     hidden_global_offset_y
      - .offset:         288
        .size:           8
        .value_kind:     hidden_global_offset_z
      - .offset:         296
        .size:           2
        .value_kind:     hidden_grid_dims
    .group_segment_fixed_size: 0
    .kernarg_segment_align: 8
    .kernarg_segment_size: 488
    .language:       OpenCL C
    .language_version:
      - 2
      - 0
    .max_flat_workgroup_size: 512
    .name:           _Z10fwd_kernelILi4ELi5EEv4Args
    .private_segment_fixed_size: 0
    .sgpr_count:     66
    .sgpr_spill_count: 0
    .symbol:         _Z10fwd_kernelILi4ELi5EEv4Args.kd
    .uniform_work_group_size: 1
    .uses_dynamic_stack: false
    .vgpr_count:     256
    .vgpr_spill_count: 0
    .wavefront_size: 64
  - .agpr_count:     0
    .args:
      - .offset:         0
        .size:           232
        .value_kind:     by_value
      - .offset:         232
        .size:           4
        .value_kind:     hidden_block_count_x
      - .offset:         236
        .size:           4
        .value_kind:     hidden_block_count_y
      - .offset:         240
        .size:           4
        .value_kind:     hidden_block_count_z
      - .offset:         244
        .size:           2
        .value_kind:     hidden_group_size_x
      - .offset:         246
        .size:           2
        .value_kind:     hidden_group_size_y
      - .offset:         248
        .size:           2
        .value_kind:     hidden_group_size_z
      - .offset:         250
        .size:           2
        .value_kind:     hidden_remainder_x
      - .offset:         252
        .size:           2
        .value_kind:     hidden_remainder_y
      - .offset:         254
        .size:           2
        .value_kind:     hidden_remainder_z
      - .offset:         272
        .size:           8
        .value_kind:     hidden_global_offset_x
      - .offset:         280
        .size:           8
        .value_kind:     hidden_global_offset_y
      - .offset:         288
        .size:           8
        .value_kind:     hidden_global_offset_z
      - .offset:         296
        .size:           2
        .value_kind:     hidden_grid_dims
      - .offset:         352
        .size:           4
        .value_kind:     hidden_dynamic_lds_size
    .group_segment_fixed_size: 0
    .kernarg_segment_align: 8
    .kernarg_segment_size: 488
    .language:       OpenCL C
    .language_version:
      - 2
      - 0
    .max_flat_workgroup_size: 512
    .name:           _Z10fwd_kernelILi5ELi6EEv4Args
    .private_segment_fixed_size: 0
    .sgpr_count:     68
    .sgpr_spill_count: 0
    .symbol:         _Z10fwd_kernelILi5ELi6EEv4Args.kd
    .uniform_work_group_size: 1
    .uses_dynamic_stack: false
    .vgpr_count:     256
    .vgpr_spill_count: 0
    .wavefront_size: 64
  - .agpr_count:     0
    .args:
      - .offset:         0
        .size:           232
        .value_kind:     by_value
      - .offset:         232
        .size:           4
        .value_kind:     hidden_block_count_x
      - .offset:         236
        .size:           4
        .value_kind:     hidden_block_count_y
      - .offset:         240
        .size:           4
        .value_kind:     hidden_block_count_z
      - .offset:         244
        .size:           2
        .value_kind:     hidden_group_size_x
      - .offset:         246
        .size:           2
        .value_kind:     hidden_group_size_y
      - .offset:         248
        .size:           2
        .value_kind:     hidden_group_size_z
      - .offset:         250
        .size:           2
        .value_kind:     hidden_remainder_x
      - .offset:         252
        .size:           2
        .value_kind:     hidden_remainder_y
      - .offset:         254
        .size:           2
        .value_kind:     hidden_remainder_z
      - .offset:         272
        .size:           8
        .value_kind:     hidden_global_offset_x
      - .offset:         280
        .size:           8
        .value_kind:     hidden_global_offset_y
      - .offset:         288
        .size:           8
        .value_kind:     hidden_global_offset_z
      - .offset:         296
        .size:           2
        .value_kind:     hidden_grid_dims
      - .offset:         352
        .size:           4
        .value_kind:     hidden_dynamic_lds_size
    .group_segment_fixed_size: 0
    .kernarg_segment_align: 8
    .kernarg_segment_size: 488
    .language:       OpenCL C
    .language_version:
      - 2
      - 0
    .max_flat_workgroup_size: 512
    .name:           _Z10fwd_kernelILi6ELi7EEv4Args
    .private_segment_fixed_size: 0
    .sgpr_count:     67
    .sgpr_spill_count: 0
    .symbol:         _Z10fwd_kernelILi6ELi7EEv4Args.kd
    .uniform_work_group_size: 1
    .uses_dynamic_stack: false
    .vgpr_count:     240
    .vgpr_spill_count: 0
    .wavefront_size: 64
  - .agpr_count:     0
    .args:
      - .offset:         0
        .size:           232
        .value_kind:     by_value
      - .offset:         232
        .size:           4
        .value_kind:     hidden_block_count_x
      - .offset:         236
        .size:           4
        .value_kind:     hidden_block_count_y
      - .offset:         240
        .size:           4
        .value_kind:     hidden_block_count_z
      - .offset:         244
        .size:           2
        .value_kind:     hidden_group_size_x
      - .offset:         246
        .size:           2
        .value_kind:     hidden_group_size_y
      - .offset:         248
        .size:           2
        .value_kind:     hidden_group_size_z
      - .offset:         250
        .size:           2
        .value_kind:     hidden_remainder_x
      - .offset:         252
        .size:           2
        .value_kind:     hidden_remainder_y
      - .offset:         254
        .size:           2
        .value_kind:     hidden_remainder_z
      - .offset:         272
        .size:           8
        .value_kind:     hidden_global_offset_x
      - .offset:         280
        .size:           8
        .value_kind:     hidden_global_offset_y
      - .offset:         288
        .size:           8
        .value_kind:     hidden_global_offset_z
      - .offset:         296
        .size:           2
        .value_kind:     hidden_grid_dims
    .group_segment_fixed_size: 0
    .kernarg_segment_align: 8
    .kernarg_segment_size: 488
    .language:       OpenCL C
    .language_version:
      - 2
      - 0
    .max_flat_workgroup_size: 512
    .name:           _Z10fwd_kernelILi7ELi8EEv4Args
    .private_segment_fixed_size: 0
    .sgpr_count:     66
    .sgpr_spill_count: 0
    .symbol:         _Z10fwd_kernelILi7ELi8EEv4Args.kd
    .uniform_work_group_size: 1
    .uses_dynamic_stack: false
    .vgpr_count:     256
    .vgpr_spill_count: 0
    .wavefront_size: 64
  - .agpr_count:     0
    .args:
      - .offset:         0
        .size:           232
        .value_kind:     by_value
      - .offset:         232
        .size:           4
        .value_kind:     hidden_block_count_x
      - .offset:         236
        .size:           4
        .value_kind:     hidden_block_count_y
      - .offset:         240
        .size:           4
        .value_kind:     hidden_block_count_z
      - .offset:         244
        .size:           2
        .value_kind:     hidden_group_size_x
      - .offset:         246
        .size:           2
        .value_kind:     hidden_group_size_y
      - .offset:         248
        .size:           2
        .value_kind:     hidden_group_size_z
      - .offset:         250
        .size:           2
        .value_kind:     hidden_remainder_x
      - .offset:         252
        .size:           2
        .value_kind:     hidden_remainder_y
      - .offset:         254
        .size:           2
        .value_kind:     hidden_remainder_z
      - .offset:         272
        .size:           8
        .value_kind:     hidden_global_offset_x
      - .offset:         280
        .size:           8
        .value_kind:     hidden_global_offset_y
      - .offset:         288
        .size:           8
        .value_kind:     hidden_global_offset_z
      - .offset:         296
        .size:           2
        .value_kind:     hidden_grid_dims
      - .offset:         352
        .size:           4
        .value_kind:     hidden_dynamic_lds_size
    .group_segment_fixed_size: 0
    .kernarg_segment_align: 8
    .kernarg_segment_size: 488
    .language:       OpenCL C
    .language_version:
      - 2
      - 0
    .max_flat_workgroup_size: 512
    .name:           _Z10fwd_kernelILi8ELi9EEv4Args
    .private_segment_fixed_size: 0
    .sgpr_count:     75
    .sgpr_spill_count: 0
    .symbol:         _Z10fwd_kernelILi8ELi9EEv4Args.kd
    .uniform_work_group_size: 1
    .uses_dynamic_stack: false
    .vgpr_count:     256
    .vgpr_spill_count: 0
    .wavefront_size: 64
  - .agpr_count:     0
    .args:
      - .offset:         0
        .size:           232
        .value_kind:     by_value
      - .offset:         232
        .size:           4
        .value_kind:     hidden_block_count_x
      - .offset:         236
        .size:           4
        .value_kind:     hidden_block_count_y
      - .offset:         240
        .size:           4
        .value_kind:     hidden_block_count_z
      - .offset:         244
        .size:           2
        .value_kind:     hidden_group_size_x
      - .offset:         246
        .size:           2
        .value_kind:     hidden_group_size_y
      - .offset:         248
        .size:           2
        .value_kind:     hidden_group_size_z
      - .offset:         250
        .size:           2
        .value_kind:     hidden_remainder_x
      - .offset:         252
        .size:           2
        .value_kind:     hidden_remainder_y
      - .offset:         254
        .size:           2
        .value_kind:     hidden_remainder_z
      - .offset:         272
        .size:           8
        .value_kind:     hidden_global_offset_x
      - .offset:         280
        .size:           8
        .value_kind:     hidden_global_offset_y
      - .offset:         288
        .size:           8
        .value_kind:     hidden_global_offset_z
      - .offset:         296
        .size:           2
        .value_kind:     hidden_grid_dims
      - .offset:         352
        .size:           4
        .value_kind:     hidden_dynamic_lds_size
    .group_segment_fixed_size: 0
    .kernarg_segment_align: 8
    .kernarg_segment_size: 488
    .language:       OpenCL C
    .language_version:
      - 2
      - 0
    .max_flat_workgroup_size: 512
    .name:           _Z10fwd_kernelILi9ELi10EEv4Args
    .private_segment_fixed_size: 0
    .sgpr_count:     82
    .sgpr_spill_count: 0
    .symbol:         _Z10fwd_kernelILi9ELi10EEv4Args.kd
    .uniform_work_group_size: 1
    .uses_dynamic_stack: false
    .vgpr_count:     200
    .vgpr_spill_count: 0
    .wavefront_size: 64
  - .agpr_count:     0
    .args:
      - .offset:         0
        .size:           232
        .value_kind:     by_value
      - .offset:         232
        .size:           4
        .value_kind:     hidden_block_count_x
      - .offset:         236
        .size:           4
        .value_kind:     hidden_block_count_y
      - .offset:         240
        .size:           4
        .value_kind:     hidden_block_count_z
      - .offset:         244
        .size:           2
        .value_kind:     hidden_group_size_x
      - .offset:         246
        .size:           2
        .value_kind:     hidden_group_size_y
      - .offset:         248
        .size:           2
        .value_kind:     hidden_group_size_z
      - .offset:         250
        .size:           2
        .value_kind:     hidden_remainder_x
      - .offset:         252
        .size:           2
        .value_kind:     hidden_remainder_y
      - .offset:         254
        .size:           2
        .value_kind:     hidden_remainder_z
      - .offset:         272
        .size:           8
        .value_kind:     hidden_global_offset_x
      - .offset:         280
        .size:           8
        .value_kind:     hidden_global_offset_y
      - .offset:         288
        .size:           8
        .value_kind:     hidden_global_offset_z
      - .offset:         296
        .size:           2
        .value_kind:     hidden_grid_dims
      - .offset:         352
        .size:           4
        .value_kind:     hidden_dynamic_lds_size
    .group_segment_fixed_size: 0
    .kernarg_segment_align: 8
    .kernarg_segment_size: 488
    .language:       OpenCL C
    .language_version:
      - 2
      - 0
    .max_flat_workgroup_size: 512
    .name:           _Z10fwd_kernelILi10ELi11EEv4Args
    .private_segment_fixed_size: 0
    .sgpr_count:     67
    .sgpr_spill_count: 0
    .symbol:         _Z10fwd_kernelILi10ELi11EEv4Args.kd
    .uniform_work_group_size: 1
    .uses_dynamic_stack: false
    .vgpr_count:     240
    .vgpr_spill_count: 0
    .wavefront_size: 64
  - .agpr_count:     0
    .args:
      - .offset:         0
        .size:           232
        .value_kind:     by_value
      - .offset:         232
        .size:           4
        .value_kind:     hidden_block_count_x
      - .offset:         236
        .size:           4
        .value_kind:     hidden_block_count_y
      - .offset:         240
        .size:           4
        .value_kind:     hidden_block_count_z
      - .offset:         244
        .size:           2
        .value_kind:     hidden_group_size_x
      - .offset:         246
        .size:           2
        .value_kind:     hidden_group_size_y
      - .offset:         248
        .size:           2
        .value_kind:     hidden_group_size_z
      - .offset:         250
        .size:           2
        .value_kind:     hidden_remainder_x
      - .offset:         252
        .size:           2
        .value_kind:     hidden_remainder_y
      - .offset:         254
        .size:           2
        .value_kind:     hidden_remainder_z
      - .offset:         272
        .size:           8
        .value_kind:     hidden_global_offset_x
      - .offset:         280
        .size:           8
        .value_kind:     hidden_global_offset_y
      - .offset:         288
        .size:           8
        .value_kind:     hidden_global_offset_z
      - .offset:         296
        .size:           2
        .value_kind:     hidden_grid_dims
    .group_segment_fixed_size: 0
    .kernarg_segment_align: 8
    .kernarg_segment_size: 488
    .language:       OpenCL C
    .language_version:
      - 2
      - 0
    .max_flat_workgroup_size: 512
    .name:           _Z10fwd_kernelILi11ELi12EEv4Args
    .private_segment_fixed_size: 0
    .sgpr_count:     66
    .sgpr_spill_count: 0
    .symbol:         _Z10fwd_kernelILi11ELi12EEv4Args.kd
    .uniform_work_group_size: 1
    .uses_dynamic_stack: false
    .vgpr_count:     256
    .vgpr_spill_count: 0
    .wavefront_size: 64
  - .agpr_count:     0
    .args:
      - .offset:         0
        .size:           232
        .value_kind:     by_value
      - .offset:         232
        .size:           4
        .value_kind:     hidden_block_count_x
      - .offset:         236
        .size:           4
        .value_kind:     hidden_block_count_y
      - .offset:         240
        .size:           4
        .value_kind:     hidden_block_count_z
      - .offset:         244
        .size:           2
        .value_kind:     hidden_group_size_x
      - .offset:         246
        .size:           2
        .value_kind:     hidden_group_size_y
      - .offset:         248
        .size:           2
        .value_kind:     hidden_group_size_z
      - .offset:         250
        .size:           2
        .value_kind:     hidden_remainder_x
      - .offset:         252
        .size:           2
        .value_kind:     hidden_remainder_y
      - .offset:         254
        .size:           2
        .value_kind:     hidden_remainder_z
      - .offset:         272
        .size:           8
        .value_kind:     hidden_global_offset_x
      - .offset:         280
        .size:           8
        .value_kind:     hidden_global_offset_y
      - .offset:         288
        .size:           8
        .value_kind:     hidden_global_offset_z
      - .offset:         296
        .size:           2
        .value_kind:     hidden_grid_dims
      - .offset:         352
        .size:           4
        .value_kind:     hidden_dynamic_lds_size
    .group_segment_fixed_size: 0
    .kernarg_segment_align: 8
    .kernarg_segment_size: 488
    .language:       OpenCL C
    .language_version:
      - 2
      - 0
    .max_flat_workgroup_size: 512
    .name:           _Z10fwd_kernelILi12ELi13EEv4Args
    .private_segment_fixed_size: 0
    .sgpr_count:     68
    .sgpr_spill_count: 0
    .symbol:         _Z10fwd_kernelILi12ELi13EEv4Args.kd
    .uniform_work_group_size: 1
    .uses_dynamic_stack: false
    .vgpr_count:     256
    .vgpr_spill_count: 0
    .wavefront_size: 64
  - .agpr_count:     0
    .args:
      - .offset:         0
        .size:           232
        .value_kind:     by_value
      - .offset:         232
        .size:           4
        .value_kind:     hidden_block_count_x
      - .offset:         236
        .size:           4
        .value_kind:     hidden_block_count_y
      - .offset:         240
        .size:           4
        .value_kind:     hidden_block_count_z
      - .offset:         244
        .size:           2
        .value_kind:     hidden_group_size_x
      - .offset:         246
        .size:           2
        .value_kind:     hidden_group_size_y
      - .offset:         248
        .size:           2
        .value_kind:     hidden_group_size_z
      - .offset:         250
        .size:           2
        .value_kind:     hidden_remainder_x
      - .offset:         252
        .size:           2
        .value_kind:     hidden_remainder_y
      - .offset:         254
        .size:           2
        .value_kind:     hidden_remainder_z
      - .offset:         272
        .size:           8
        .value_kind:     hidden_global_offset_x
      - .offset:         280
        .size:           8
        .value_kind:     hidden_global_offset_y
      - .offset:         288
        .size:           8
        .value_kind:     hidden_global_offset_z
      - .offset:         296
        .size:           2
        .value_kind:     hidden_grid_dims
      - .offset:         352
        .size:           4
        .value_kind:     hidden_dynamic_lds_size
    .group_segment_fixed_size: 0
    .kernarg_segment_align: 8
    .kernarg_segment_size: 488
    .language:       OpenCL C
    .language_version:
      - 2
      - 0
    .max_flat_workgroup_size: 512
    .name:           _Z10fwd_kernelILi13ELi14EEv4Args
    .private_segment_fixed_size: 0
    .sgpr_count:     67
    .sgpr_spill_count: 0
    .symbol:         _Z10fwd_kernelILi13ELi14EEv4Args.kd
    .uniform_work_group_size: 1
    .uses_dynamic_stack: false
    .vgpr_count:     240
    .vgpr_spill_count: 0
    .wavefront_size: 64
  - .agpr_count:     0
    .args:
      - .offset:         0
        .size:           232
        .value_kind:     by_value
      - .offset:         232
        .size:           4
        .value_kind:     hidden_block_count_x
      - .offset:         236
        .size:           4
        .value_kind:     hidden_block_count_y
      - .offset:         240
        .size:           4
        .value_kind:     hidden_block_count_z
      - .offset:         244
        .size:           2
        .value_kind:     hidden_group_size_x
      - .offset:         246
        .size:           2
        .value_kind:     hidden_group_size_y
      - .offset:         248
        .size:           2
        .value_kind:     hidden_group_size_z
      - .offset:         250
        .size:           2
        .value_kind:     hidden_remainder_x
      - .offset:         252
        .size:           2
        .value_kind:     hidden_remainder_y
      - .offset:         254
        .size:           2
        .value_kind:     hidden_remainder_z
      - .offset:         272
        .size:           8
        .value_kind:     hidden_global_offset_x
      - .offset:         280
        .size:           8
        .value_kind:     hidden_global_offset_y
      - .offset:         288
        .size:           8
        .value_kind:     hidden_global_offset_z
      - .offset:         296
        .size:           2
        .value_kind:     hidden_grid_dims
    .group_segment_fixed_size: 0
    .kernarg_segment_align: 8
    .kernarg_segment_size: 488
    .language:       OpenCL C
    .language_version:
      - 2
      - 0
    .max_flat_workgroup_size: 512
    .name:           _Z10fwd_kernelILi14ELi15EEv4Args
    .private_segment_fixed_size: 0
    .sgpr_count:     66
    .sgpr_spill_count: 0
    .symbol:         _Z10fwd_kernelILi14ELi15EEv4Args.kd
    .uniform_work_group_size: 1
    .uses_dynamic_stack: false
    .vgpr_count:     256
    .vgpr_spill_count: 0
    .wavefront_size: 64
